# GLA scan: output-tile flush stores issued at the head of section C (VALU-bound) instead of in section A next to the LDS-DMA loads
# speedup vs baseline: 1.0115x; 1.0115x over previous
; __device__ __forceinline__ int crow(int r, int hi) { return (r & 3) + 8 * (r >> 2) + 4 * hi; }
; __device__ __forceinline__ int v_st(int k, int c) { const int kk = (k & ~0xC) | ((k & 4) << 1) | ((k & 8) >> 1); return ((kk >> 3) * 4 + (c >> 5)) * 512 + ((kk & 7) * 32 + (c & 31)) * 2; }
; #define OPAQUE_TID(name) int name = MK_TID; asm volatile("" : "+v"(name))
; #define GLA_FLUSH() do { if (pend_cc >= 0) { OPAQUE_TID(tf_); const size_t rl0_ = (size_t)b * T + (size_t)(pend_cc - 4) * 64; \
;       _Pragma("unroll") for (int p = 0; p < 4; ++p) { const int idx_ = p * 512 + tf_, i_ = idx_ >> 5, c16_ = idx_ & 31; \
;           *(v4u*)(OUT + (rl0_ + (dir ? 63 - i_ : i_)) * 1024 + h * 256 + c16_ * 8) = *(const v4u*)(ot + i_ * 256 + c16_ * 8); } } } while (0)
; __device__ __forceinline__ void scan_unit(const int unit, const Args& a, unsigned char* lds, const int mk_wid) {
;     ...
;         GLA_FLUSH();
;         { OPAQUE_TID(t_);
; #pragma unroll
;           for (int p = 0; p < 2; ++p) { const int i_ = p * 32 + (t_ >> 4), c_ = (t_ & 15) * 8; *(bf16x8*)(qe + i_ * QP + c_) = qraw[p]; *(bf16x8*)(ke + i_ * QP + c_) = kraw[p]; }
; #pragma unroll
;           for (int p = 0; p < 4; ++p) { const int i_ = p * 16 + (t_ >> 5), c8 = t_ & 31; *(bf16x8*)(lds + L_V + (c8 >> 4) * 16384 + v_st(i_, (c8 & 15) * 8)) = vraw[p]; }
;           if (t_ < 128) *(bf16x8*)(lds + L_LR + (t_ >> 1) * 32 + (t_ & 1) * 16) = lraw; }
;         __syncthreads();
;         { OPAQUE_TID(t_); const int lane = t_ & 63, r32 = lane & 31, hi = lane >> 5; const int tt = wid >> 2, ct = wid & 3;
;           const bf16x8 af = *(const bf16x8*)(lds + L_LR + (tt * 32 + r32) * 32 + hi * 16);
;           const f32x16 z = __builtin_amdgcn_mfma_f32_32x32x16_bf16(af, upf, f32x16{}, 0, 0, 0);
;           float* lw = las + (tt * 32 + 4 * hi) * 128 + ct * 32 + r32;
; #pragma unroll
;           for (int r = 0; r < 16; ++r) { const float zz = z[r] + biasc;
;               lw[crow(r, 0) * 128] = (fminf(zz, 0.f) - __builtin_amdgcn_logf(1.f + __builtin_amdgcn_exp2f(-1.4426950408889634f * fabsf(zz))) * 0.6931471805599453f) * (1.f / 16.f); } }
.Lscan_noflrd:
	v_add_u32_e32 v66, s96, v247
	v_add_u32_e32 v67, s96, v248
	v_add_u32_e32 v68, s96, v249
	v_add_u32_e32 v69, s96, v250
	s_mov_b32 m0, s97
	s_nop 0
	global_load_lds_dwordx4 v66, s[16:17]
	s_add_i32 m0, s97, 0x400
	s_nop 0
	global_load_lds_dwordx4 v67, s[16:17]
	s_add_i32 m0, s97, 0x800
	s_nop 0
	global_load_lds_dwordx4 v68, s[16:17]
	s_add_i32 m0, s97, 0xc00
	s_nop 0
	global_load_lds_dwordx4 v69, s[16:17]
	s_cmp_lt_i32 s34, 0
	s_cbranch_scc1 .Lscan_noflush
	s_ashr_i32 s35, s34, 31
	s_lshl_b64 s[26:27], s[34:35], 6
	s_add_u32 s26, s26, s20
	s_addc_u32 s27, s27, s21
	s_add_u32 s26, s26, 0xffffff00
	s_addc_u32 s27, s27, -1
	s_lshl_b64 s[26:27], s[26:27], 11
	s_add_u32 s26, s26, s18
	s_addc_u32 s27, s27, s19
	s_movk_i32 s98, 0x4000
	s_movk_i32 s99, 0xc000
	s_bitcmp1_b32 s8, 0
	s_cselect_b32 s98, s99, s98
	v_add_u32_e32 v165, s98, v252
	v_add_u32_e32 v166, s98, v165
	v_add_u32_e32 v167, s98, v166
.Lscan_noflush:
	v_mbcnt_lo_u32_b32 v64, -1, 0
	v_mbcnt_hi_u32_b32 v64, -1, v64
	s_nop 0
	v_add_u32_e32 v64, s72, v64
	s_nop 0
	v_and_b32_e32 v68, 31, v64
	v_bfe_u32 v69, v64, 5, 1
	v_lshlrev_b32_e32 v69, 11, v69
	v_lshlrev_b32_e32 v68, 2, v68
	v_add3_u32 v80, s45, v69, v68
	v_mfma_f32_32x32x16_bf16 v[64:79], v[96:99], v[108:111], 0
	s_mov_b32 s96, 1.0
	s_mov_b32 s97, 0xbf317218
	s_mov_b32 s98, 0x3db8aa3b
	s_nop 11
	v_pk_add_f32 v[64:65], v[64:65], v[156:157] op_sel_hi:[1,0]
	v_pk_add_f32 v[66:67], v[66:67], v[156:157] op_sel_hi:[1,0]
	v_pk_add_f32 v[68:69], v[68:69], v[156:157] op_sel_hi:[1,0]
	v_pk_add_f32 v[70:71], v[70:71], v[156:157] op_sel_hi:[1,0]
	v_mul_f32_e64 v82, |v64|, s54
	v_mul_f32_e64 v83, |v65|, s54
	v_mul_f32_e64 v84, |v66|, s54
	v_mul_f32_e64 v85, |v67|, s54
	v_mul_f32_e64 v86, |v68|, s54
	v_mul_f32_e64 v87, |v69|, s54
	v_mul_f32_e64 v88, |v70|, s54
	v_mul_f32_e64 v89, |v71|, s54
	v_exp_f32_e32 v82, v82
	v_exp_f32_e32 v83, v83
	v_exp_f32_e32 v84, v84
	v_exp_f32_e32 v85, v85
	v_exp_f32_e32 v86, v86
	v_exp_f32_e32 v87, v87
	v_exp_f32_e32 v88, v88
	v_exp_f32_e32 v89, v89
	v_pk_add_f32 v[82:83], v[82:83], s[96:97] op_sel_hi:[1,0]
	v_pk_add_f32 v[84:85], v[84:85], s[96:97] op_sel_hi:[1,0]
	v_pk_add_f32 v[86:87], v[86:87], s[96:97] op_sel_hi:[1,0]
	v_pk_add_f32 v[88:89], v[88:89], s[96:97] op_sel_hi:[1,0]
	v_log_f32_e32 v82, v82
	v_log_f32_e32 v83, v83
	v_log_f32_e32 v84, v84
	v_log_f32_e32 v85, v85
	v_log_f32_e32 v86, v86
	v_log_f32_e32 v87, v87
	v_log_f32_e32 v88, v88
	v_log_f32_e32 v89, v89
	v_min_f32_e32 v64, 0, v64
	v_min_f32_e32 v65, 0, v65
	v_min_f32_e32 v66, 0, v66
	v_min_f32_e32 v67, 0, v67
	v_min_f32_e32 v68, 0, v68
	v_min_f32_e32 v69, 0, v69
	v_min_f32_e32 v70, 0, v70
	v_min_f32_e32 v71, 0, v71
	v_pk_fma_f32 v[64:65], v[82:83], s[96:97], v[64:65] op_sel:[0,1,0] op_sel_hi:[1,1,1]
	v_pk_fma_f32 v[66:67], v[84:85], s[96:97], v[66:67] op_sel:[0,1,0] op_sel_hi:[1,1,1]
	v_pk_fma_f32 v[68:69], v[86:87], s[96:97], v[68:69] op_sel:[0,1,0] op_sel_hi:[1,1,1]
	v_pk_fma_f32 v[70:71], v[88:89], s[96:97], v[70:71] op_sel:[0,1,0] op_sel_hi:[1,1,1]
	v_pk_mul_f32 v[64:65], v[64:65], s[98:99] op_sel_hi:[1,0]
	v_pk_mul_f32 v[66:67], v[66:67], s[98:99] op_sel_hi:[1,0]
	v_pk_mul_f32 v[68:69], v[68:69], s[98:99] op_sel_hi:[1,0]
	v_pk_mul_f32 v[70:71], v[70:71], s[98:99] op_sel_hi:[1,0]
	ds_write2st64_b32 v80, v64, v65 offset1:2
	ds_write2st64_b32 v80, v66, v67 offset0:4 offset1:6
	ds_write2st64_b32 v80, v68, v69 offset0:16 offset1:18
	ds_write2st64_b32 v80, v70, v71 offset0:20 offset1:22
	v_pk_add_f32 v[72:73], v[72:73], v[156:157] op_sel_hi:[1,0]
	v_pk_add_f32 v[74:75], v[74:75], v[156:157] op_sel_hi:[1,0]
	v_pk_add_f32 v[76:77], v[76:77], v[156:157] op_sel_hi:[1,0]
	v_pk_add_f32 v[78:79], v[78:79], v[156:157] op_sel_hi:[1,0]
	v_mul_f32_e64 v82, |v72|, s54
	v_mul_f32_e64 v83, |v73|, s54
	v_mul_f32_e64 v84, |v74|, s54
	v_mul_f32_e64 v85, |v75|, s54
	v_mul_f32_e64 v86, |v76|, s54
	v_mul_f32_e64 v87, |v77|, s54
	v_mul_f32_e64 v88, |v78|, s54
	v_mul_f32_e64 v89, |v79|, s54
	v_exp_f32_e32 v82, v82
	v_exp_f32_e32 v83, v83
	v_exp_f32_e32 v84, v84
	v_exp_f32_e32 v85, v85
	v_exp_f32_e32 v86, v86
	v_exp_f32_e32 v87, v87
	v_exp_f32_e32 v88, v88
	v_exp_f32_e32 v89, v89
	v_pk_add_f32 v[82:83], v[82:83], s[96:97] op_sel_hi:[1,0]
	v_pk_add_f32 v[84:85], v[84:85], s[96:97] op_sel_hi:[1,0]
	v_pk_add_f32 v[86:87], v[86:87], s[96:97] op_sel_hi:[1,0]
	v_pk_add_f32 v[88:89], v[88:89], s[96:97] op_sel_hi:[1,0]
	v_log_f32_e32 v82, v82
	v_log_f32_e32 v83, v83
	v_log_f32_e32 v84, v84
	v_log_f32_e32 v85, v85
	v_log_f32_e32 v86, v86
	v_log_f32_e32 v87, v87
	v_log_f32_e32 v88, v88
	v_log_f32_e32 v89, v89
	v_min_f32_e32 v72, 0, v72
	v_min_f32_e32 v73, 0, v73
	v_min_f32_e32 v74, 0, v74
	v_min_f32_e32 v75, 0, v75
	v_min_f32_e32 v76, 0, v76
	v_min_f32_e32 v77, 0, v77
	v_min_f32_e32 v78, 0, v78
	v_min_f32_e32 v79, 0, v79
	v_pk_fma_f32 v[72:73], v[82:83], s[96:97], v[72:73] op_sel:[0,1,0] op_sel_hi:[1,1,1]
	v_pk_fma_f32 v[74:75], v[84:85], s[96:97], v[74:75] op_sel:[0,1,0] op_sel_hi:[1,1,1]
	v_pk_fma_f32 v[76:77], v[86:87], s[96:97], v[76:77] op_sel:[0,1,0] op_sel_hi:[1,1,1]
	v_pk_fma_f32 v[78:79], v[88:89], s[96:97], v[78:79] op_sel:[0,1,0] op_sel_hi:[1,1,1]
	v_pk_mul_f32 v[72:73], v[72:73], s[98:99] op_sel_hi:[1,0]
	v_pk_mul_f32 v[74:75], v[74:75], s[98:99] op_sel_hi:[1,0]
	v_pk_mul_f32 v[76:77], v[76:77], s[98:99] op_sel_hi:[1,0]
	v_pk_mul_f32 v[78:79], v[78:79], s[98:99] op_sel_hi:[1,0]
	ds_write2st64_b32 v80, v72, v73 offset0:32 offset1:34
	ds_write2st64_b32 v80, v74, v75 offset0:36 offset1:38
	ds_write2st64_b32 v80, v76, v77 offset0:48 offset1:50
	ds_write2st64_b32 v80, v78, v79 offset0:52 offset1:54
	v_pk_add_f32 v[82:83], v[64:65], v[66:67]
	v_pk_add_f32 v[84:85], v[68:69], v[70:71]
	v_pk_add_f32 v[86:87], v[72:73], v[74:75]
	v_pk_add_f32 v[88:89], v[76:77], v[78:79]
	v_add_f32_e32 v82, v82, v83
	v_add_f32_e32 v84, v84, v85
	v_add_f32_e32 v86, v86, v87
	v_add_f32_e32 v88, v88, v89
	ds_write2st64_b32 v169, v82, v84 offset1:4
	ds_write2st64_b32 v169, v86, v88 offset0:8 offset1:12
	s_waitcnt lgkmcnt(0)
	s_barrier
; #define OPAQUE_TID(name) int name = MK_TID; asm volatile("" : "+v"(name))
; __device__ __forceinline__ void scan_unit(const int unit, const Args& a, unsigned char* lds, const int mk_wid) {
;     ...
;         { OPAQUE_TID(t_); const int c = t_ & 127, g = t_ >> 7;
;           float bl[16]; float run = 0.f;
;           { const float* lp = las + (g * 16) * 128 + c;
; #pragma unroll
;             for (int ii = 0; ii < 16; ++ii) { run += lp[ii * 128]; bl[ii] = run; } }
;           gs[g * 128 + c] = run;
;           __syncthreads();
;           const float g0 = gs[c], g1 = gs[128 + c], g2 = gs[256 + c], g3 = gs[384 + c];
;           const float off = (g > 0 ? g0 : 0.f) + (g > 1 ? g1 : 0.f) + (g > 2 ? g2 : 0.f);
;           const float btot = (g0 + g1) + (g2 + g3);
;           const float dlc = __builtin_amdgcn_exp2f(btot * 1.4426950408889634f);
;           if (g == 0) dl[c] = dlc;
	v_mbcnt_lo_u32_b32 v64, -1, 0
	v_mbcnt_hi_u32_b32 v64, -1, v64
	s_lshl_b32 s96, s70, 12
	s_add_i32 s96, s96, s9
	v_lshl_add_u32 v65, v64, 3, s96
	v_lshlrev_b32_e32 v67, 3, v64
	v_add_u32_e32 v67, 0x20000, v67
	ds_read2st64_b64 v[186:189], v67 offset1:1
	ds_read2st64_b64 v[190:193], v67 offset0:2 offset1:3
	ds_read2st64_b64 v[194:197], v67 offset0:4 offset1:5
	ds_read2st64_b64 v[198:201], v67 offset0:6 offset1:7
	ds_read2st64_b64 v[202:205], v67 offset0:8 offset1:9
	ds_read2st64_b64 v[206:209], v67 offset0:10 offset1:11
	ds_read2st64_b64 v[210:213], v67 offset0:12 offset1:13
	ds_read2st64_b64 v[214:217], v67 offset0:14 offset1:15
	ds_read2st64_b64 v[170:173], v65 offset1:1
	ds_read2st64_b64 v[174:177], v65 offset0:2 offset1:3
	ds_read2st64_b64 v[178:181], v65 offset0:4 offset1:5
	ds_read2st64_b64 v[182:185], v65 offset0:6 offset1:7
	s_cmp_lt_i32 s34, 0
	s_cbranch_scc1 .Lscan_nofl2
	global_store_dwordx4 v252, v[112:115], s[26:27]
	global_store_dwordx4 v165, v[116:119], s[26:27]
	global_store_dwordx4 v166, v[120:123], s[26:27]
	global_store_dwordx4 v167, v[124:127], s[26:27]
.Lscan_nofl2:
	s_waitcnt lgkmcnt(4)
	v_pk_add_f32 v[72:73], v[186:187], v[188:189]
	v_pk_add_f32 v[74:75], v[190:191], v[192:193]
	v_pk_add_f32 v[76:77], v[194:195], v[196:197]
	v_pk_add_f32 v[78:79], v[198:199], v[200:201]
	v_pk_add_f32 v[80:81], v[202:203], v[204:205]
	v_pk_add_f32 v[82:83], v[206:207], v[208:209]
	v_pk_add_f32 v[84:85], v[210:211], v[212:213]
	v_pk_add_f32 v[86:87], v[214:215], v[216:217]
	v_pk_mul_f32 v[88:89], v[238:239], v[72:73] op_sel:[0,0] op_sel_hi:[0,1]
	v_pk_fma_f32 v[88:89], v[238:239], v[74:75], v[88:89] op_sel:[1,0,0] op_sel_hi:[1,1,1]
	v_pk_fma_f32 v[88:89], v[240:241], v[76:77], v[88:89] op_sel:[0,0,0] op_sel_hi:[0,1,1]
	v_pk_fma_f32 v[88:89], v[240:241], v[78:79], v[88:89] op_sel:[1,0,0] op_sel_hi:[1,1,1]
	v_pk_fma_f32 v[88:89], v[242:243], v[80:81], v[88:89] op_sel:[0,0,0] op_sel_hi:[0,1,1]
	v_pk_fma_f32 v[88:89], v[242:243], v[82:83], v[88:89] op_sel:[1,0,0] op_sel_hi:[1,1,1]
	v_pk_fma_f32 v[88:89], v[244:245], v[84:85], v[88:89] op_sel:[0,0,0] op_sel_hi:[0,1,1]
	v_pk_add_f32 v[90:91], v[72:73], v[74:75]
	v_pk_add_f32 v[90:91], v[90:91], v[76:77]
	v_pk_add_f32 v[90:91], v[90:91], v[78:79]
	v_pk_add_f32 v[90:91], v[90:91], v[80:81]
	v_pk_add_f32 v[90:91], v[90:91], v[82:83]
	v_pk_add_f32 v[90:91], v[90:91], v[84:85]
	v_pk_add_f32 v[90:91], v[90:91], v[86:87]
	v_mov_b64_e32 v[92:93], v[90:91]
	v_exp_f32_e32 v92, v92
	v_exp_f32_e32 v93, v93
	s_waitcnt lgkmcnt(0)
	v_pk_add_f32 v[170:171], v[170:171], v[88:89]
	v_pk_add_f32 v[172:173], v[172:173], v[170:171]
	v_pk_add_f32 v[174:175], v[174:175], v[172:173]
	v_pk_add_f32 v[176:177], v[176:177], v[174:175]
	v_pk_add_f32 v[178:179], v[178:179], v[176:177]
	v_pk_add_f32 v[180:181], v[180:181], v[178:179]
	v_pk_add_f32 v[182:183], v[182:183], v[180:181]
	v_pk_add_f32 v[184:185], v[184:185], v[182:183]
	v_exp_f32_e32 v170, v170
	v_exp_f32_e32 v171, v171
	v_exp_f32_e32 v172, v172
	v_exp_f32_e32 v173, v173
	v_exp_f32_e32 v174, v174
	v_exp_f32_e32 v175, v175
	v_exp_f32_e32 v176, v176
	v_exp_f32_e32 v177, v177
	v_exp_f32_e32 v178, v178
	v_exp_f32_e32 v179, v179
	v_exp_f32_e32 v180, v180
	v_exp_f32_e32 v181, v181
	v_exp_f32_e32 v182, v182
	v_exp_f32_e32 v183, v183
	v_exp_f32_e32 v184, v184
	v_exp_f32_e32 v185, v185
	v_rcp_f32_e32 v186, v170
	v_rcp_f32_e32 v187, v171
	v_rcp_f32_e32 v188, v172
	v_rcp_f32_e32 v189, v173
	v_rcp_f32_e32 v190, v174
	v_rcp_f32_e32 v191, v175
	v_rcp_f32_e32 v192, v176
	v_rcp_f32_e32 v193, v177
	v_rcp_f32_e32 v194, v178
	v_rcp_f32_e32 v195, v179
	v_rcp_f32_e32 v196, v180
	v_rcp_f32_e32 v197, v181
	v_rcp_f32_e32 v198, v182
	v_rcp_f32_e32 v199, v183
	v_rcp_f32_e32 v200, v184
	v_rcp_f32_e32 v201, v185
	s_mov_b32 s96, 0x3db504f3
	s_mov_b32 s97, s96
	v_pk_mul_f32 v[170:171], v[170:171], s[96:97]
	v_pk_mul_f32 v[172:173], v[172:173], s[96:97]
	v_pk_mul_f32 v[174:175], v[174:175], s[96:97]
	v_pk_mul_f32 v[176:177], v[176:177], s[96:97]
	v_pk_mul_f32 v[178:179], v[178:179], s[96:97]
	v_pk_mul_f32 v[180:181], v[180:181], s[96:97]
	v_pk_mul_f32 v[182:183], v[182:183], s[96:97]
	v_pk_mul_f32 v[184:185], v[184:185], s[96:97]
	s_cmp_lg_u32 s70, 0
	s_cbranch_scc1 .Lscan_c2_nodl
	v_lshlrev_b32_e32 v70, 3, v64
	v_add_u32_e32 v70, 0x1fc00, v70
	ds_write_b64 v70, v[92:93]
